# attention: next K/V tile staged into LDS mid-PV (after the 4th P.V MFMA) instead of at the loop tail before the barrier, on v123
# baseline (speedup 1.0000x reference)
.LBB0_1801:
	v_exp_f32_e32 v188, v66
	v_exp_f32_e32 v189, v50
	v_exp_f32_e32 v0, v67
	v_exp_f32_e32 v50, v51
	v_exp_f32_e32 v190, v52
	v_add_f32_e32 v51, v189, v188
	v_exp_f32_e32 v80, v80
	v_add_f32_e32 v66, v50, v0
	v_add_f32_e32 v67, v51, v1
	v_exp_f32_e32 v51, v68
	v_add_f32_e32 v67, v66, v67
	v_exp_f32_e32 v66, v69
	v_exp_f32_e32 v68, v53
	v_add_f32_e32 v69, v190, v51
	v_cvt_pk_bf16_f32 v50, v189, v50
	v_add_f32_e32 v52, v68, v66
	v_add_f32_e32 v53, v69, v67
	s_nop 0
	v_add_f32_e32 v179, v52, v53
	v_exp_f32_e32 v67, v70
	v_exp_f32_e32 v69, v54
	v_exp_f32_e32 v178, v71
	v_exp_f32_e32 v70, v55
	v_exp_f32_e32 v55, v72
	v_add_f32_e32 v71, v69, v67
	v_exp_f32_e32 v72, v57
	v_add_f32_e32 v52, v70, v178
	v_add_f32_e32 v53, v71, v179
	v_exp_f32_e32 v71, v56
	v_add_f32_e32 v181, v52, v53
	v_exp_f32_e32 v180, v73
	v_exp_f32_e32 v179, v58
	v_add_f32_e32 v73, v71, v55
	v_cvt_pk_bf16_f32 v54, v67, v178
	v_add_f32_e32 v52, v72, v180
	v_add_f32_e32 v53, v73, v181
	v_exp_f32_e32 v73, v74
	v_add_f32_e32 v183, v52, v53
	v_exp_f32_e32 v182, v75
	v_exp_f32_e32 v74, v59
	v_add_f32_e32 v75, v179, v73
	v_exp_f32_e32 v181, v60
	v_cvt_pk_bf16_f32 v55, v55, v180
	v_add_f32_e32 v52, v74, v182
	v_add_f32_e32 v53, v75, v183
	v_exp_f32_e32 v75, v76
	v_add_f32_e32 v185, v52, v53
	v_exp_f32_e32 v184, v77
	v_exp_f32_e32 v76, v61
	v_add_f32_e32 v77, v181, v75
	v_exp_f32_e32 v183, v62
	v_add3_u32 v62, s56, v208, v120
	v_add_f32_e32 v52, v76, v184
	v_add_f32_e32 v53, v77, v185
	v_exp_f32_e32 v77, v78
	v_add_f32_e32 v187, v52, v53
	v_cvt_pk_bf16_f32 v52, v188, v0
	v_add_u32_e32 v0, 0x3000, v62
	v_cvt_pk_bf16_f32 v53, v51, v66
	ds_read2_b64 v[56:59], v0 offset0:128 offset1:130
	v_exp_f32_e32 v186, v79
	v_exp_f32_e32 v66, v63
	v_add_f32_e32 v67, v183, v77
	s_waitcnt lgkmcnt(0)
	v_mfma_f32_32x32x16_bf16 v[18:33], v[52:55], v[56:59], v[18:33]
	v_add_f32_e64 v60, v66, v186
	v_add_f32_e64 v61, v67, v187
	v_add_u32_e32 v67, 0x4000, v62
	ds_read2_b64 v[56:59], v67 offset0:192 offset1:194
	v_add_f32_e64 v79, v60, v61
	v_exp_f32_e32 v78, v81
	ds_read2_b64 v[60:63], v0 offset0:132 offset1:134
	v_cvt_pk_bf16_f32 v51, v190, v68
	s_waitcnt lgkmcnt(1)
	v_mfma_f32_32x32x16_bf16 v[2:17], v[52:55], v[56:59], v[2:17]
	v_cvt_pk_bf16_f32 v52, v73, v182
	v_cvt_pk_bf16_f32 v53, v75, v184
	v_cvt_pk_bf16_f32 v54, v77, v186
	v_cvt_pk_bf16_f32 v55, v80, v78
	ds_read2_b64 v[56:59], v67 offset0:196 offset1:198
	s_waitcnt lgkmcnt(1)
	v_mfma_f32_32x32x16_bf16 v[18:33], v[52:55], v[60:63], v[18:33]
	s_waitcnt lgkmcnt(0)
	v_mfma_f32_32x32x16_bf16 v[2:17], v[52:55], v[56:59], v[2:17]
	s_andn2_b64 vcc, exec, s[8:9]
	s_cbranch_vccnz .Lattn_stage_done
	s_bitcmp1_b32 s55, 0
	s_cselect_b32 s10, 0x5800, 0
	v_add_u32_e32 v250, s10, v128
	v_add_u32_e32 v251, s10, v164
	v_add_u32_e32 v252, s10, v129
	s_waitcnt vmcnt(1)
	ds_write_b128 v250, v[110:113]
	s_waitcnt vmcnt(0)
	ds_write_b128 v251, v[114:117] offset:13312
	s_and_saveexec_b64 s[100:101], s[4:5]
	ds_write_b128 v252, v[106:109] offset:128
	s_or_b64 exec, exec, s[100:101]
.Lattn_stage_done:
	v_cvt_pk_bf16_f32 v52, v69, v70
	v_cvt_pk_bf16_f32 v53, v71, v72
	ds_read2_b64 v[54:57], v0 offset0:136 offset1:138
	v_exp_f32_e32 v59, v64
	v_exp_f32_e32 v58, v65
	s_waitcnt lgkmcnt(0)
	v_mfma_f32_32x32x16_bf16 v[18:33], v[50:53], v[54:57], v[18:33]
	ds_read2_b64 v[54:57], v67 offset0:200 offset1:202
	s_waitcnt lgkmcnt(0)
	v_mfma_f32_32x32x16_bf16 v[2:17], v[50:53], v[54:57], v[2:17]
	v_cvt_pk_bf16_f32 v50, v179, v74
	v_cvt_pk_bf16_f32 v51, v181, v76
	v_cvt_pk_bf16_f32 v52, v183, v66
	v_cvt_pk_bf16_f32 v53, v59, v58
	ds_read2_b64 v[54:57], v0 offset0:140 offset1:142
	v_add_f32_e32 v59, v59, v80
	v_add_f32_e32 v58, v58, v78
	v_add_f32_e32 v59, v59, v79
	s_waitcnt lgkmcnt(0)
	v_mfma_f32_32x32x16_bf16 v[18:33], v[50:53], v[54:57], v[18:33]
	ds_read2_b64 v[54:57], v67 offset0:204 offset1:206
	v_add_f32_e32 v0, v58, v59
	v_add_f32_e32 v224, v224, v0
	s_waitcnt lgkmcnt(0)
	v_mfma_f32_32x32x16_bf16 v[2:17], v[50:53], v[54:57], v[2:17]
	s_branch .LBB0_1790
